# phase D: GELU of the activation 8 k-steps ahead interleaved into the f32 MFMA groups (MFMA shadow) instead of a separate GELU pass
# speedup vs baseline: 1.0148x; 1.0148x over previous
; #define INP(k) ({ int k_ = (k); LAUNDER_S(k_); (const float*)(const GAS float*)P.in[k_]; })
; __global__ void __launch_bounds__(512, 2) hybrid_fwd(Params P) {
;     ...
;         { PHASE_BEGIN
;             const int gwave = bx * 8 + wave, nwaves = G * 8;
;             const float* cw2 = INP(10) + (size_t)L * 2 * 256 * 64; const float* nkn = INP(7) + L * 192;
;             bf16_t* KC = (bf16_t*)(ws + WS_KC); bf16_t* VCT = (bf16_t*)(ws + WS_VCT);
;             for (int row = gwave; row < 8192; row += nwaves) { const int kv = row >> 12, rr = row & 4095, bg = rr >> 9, n = rr & 511;
;                 f32x4 hv = *(const f32x4*)((const float*)(ws + WS_SMALL) + kv * 256 + 4 * lane);
;                 { const float* pp = (const float*)(ws + WS_H) + ((size_t)(kv * 4) * 4096 + rr) * 256 + 4 * lane;
; #pragma unroll
;                     for (int ks = 0; ks < 4; ++ks) hv += *(const f32x4*)(pp + (size_t)ks * 4096 * 256);
.LBB0_777:
	s_or_b64 exec, exec, s[4:5]
	v_readlane_b32 s4, v255, 17
	s_mov_b32 s6, s4
	s_mov_b64 s[4:5], s[58:59]
	s_mov_b32 s14, s69
	s_mov_b32 s15, s2
	v_mov_b32_e32 v0, v146
	s_barrier
	v_readfirstlane_b32 s7, v0
	s_lshr_b32 s7, s7, 6
	s_cmp_gt_u32 s7, 1
	s_cbranch_scc1 .LBB0_784
	s_load_dwordx2 s[10:11], s[0:1], 0x50
	s_load_dwordx2 s[12:13], s[0:1], 0x38
	s_lshl_b32 s8, s15, 1
	s_add_u32 s8, s8, s7
	s_lshr_b32 s9, s8, 8
	s_and_b32 s8, s8, 0xff
	s_lshl_b32 s8, s8, 4
	v_and_b32_e32 v244, 63, v0
	v_and_b32_e32 v245, 15, v244
	v_lshrrev_b32_e32 v246, 4, v244
	v_lshlrev_b32_e32 v248, 8, v246
	v_lshl_add_u32 v247, v245, 10, v248
	v_lshlrev_b32_e32 v250, 4, v245
	v_lshl_add_u32 v249, v246, 14, v250
	v_lshlrev_b32_e32 v251, 3, v245
	v_lshl_add_u32 v251, v246, 9, v251
	v_lshlrev_b32_e32 v252, 3, v246
	v_lshl_add_u32 v252, v245, 12, v252
	s_lshl_b32 s16, s9, 10
	s_add_u32 s16, s16, 0x2400000
	s_add_u32 s98, s4, s16
	s_addc_u32 s99, s5, 0
	s_lshl_b32 s16, s9, 24
	s_lshl_b32 s18, s8, 10
	s_add_u32 s16, s16, s18
	s_add_u32 s16, s16, 0x3100000
	s_add_u32 s14, s4, s16
	s_addc_u32 s15, s5, 0
	s_waitcnt lgkmcnt(0)
	s_lshl_b32 s16, s6, 17
	s_lshl_b32 s18, s9, 16
	s_add_u32 s16, s16, s18
	s_add_u32 s10, s10, s16
	s_addc_u32 s11, s11, 0
	s_mul_i32 s16, s6, 0x300
	s_add_u32 s12, s12, s16
	s_addc_u32 s13, s13, 0
	global_load_dwordx4 v[240:243], v250, s[12:13]
	global_load_dwordx4 v[0:3], v248, s[98:99]
	global_load_dwordx4 v[4:7], v248, s[98:99] offset:16
	global_load_dwordx4 v[8:11], v248, s[98:99] offset:32
	global_load_dwordx4 v[12:15], v248, s[98:99] offset:48
	global_load_dwordx4 v[16:19], v248, s[98:99] offset:64
	global_load_dwordx4 v[20:23], v248, s[98:99] offset:80
	global_load_dwordx4 v[24:27], v248, s[98:99] offset:96
	global_load_dwordx4 v[28:31], v248, s[98:99] offset:112
	global_load_dwordx4 v[32:35], v248, s[98:99] offset:128
	global_load_dwordx4 v[36:39], v248, s[98:99] offset:144
	global_load_dwordx4 v[40:43], v248, s[98:99] offset:160
	global_load_dwordx4 v[44:47], v248, s[98:99] offset:176
	global_load_dwordx4 v[48:51], v248, s[98:99] offset:192
	global_load_dwordx4 v[52:55], v248, s[98:99] offset:208
	global_load_dwordx4 v[56:59], v248, s[98:99] offset:224
	global_load_dwordx4 v[60:63], v248, s[98:99] offset:240
	global_load_dwordx4 v[82:85], v247, s[14:15]
	global_load_dwordx4 v[86:89], v247, s[14:15] offset:16
	global_load_dwordx4 v[90:93], v247, s[14:15] offset:32
	global_load_dwordx4 v[94:97], v247, s[14:15] offset:48
	global_load_dwordx4 v[98:101], v247, s[14:15] offset:64
	global_load_dwordx4 v[102:105], v247, s[14:15] offset:80
	global_load_dwordx4 v[106:109], v247, s[14:15] offset:96
	global_load_dwordx4 v[110:113], v247, s[14:15] offset:112
	global_load_dwordx4 v[114:117], v247, s[14:15] offset:128
	global_load_dwordx4 v[118:121], v247, s[14:15] offset:144
	global_load_dwordx4 v[122:125], v247, s[14:15] offset:160
	global_load_dwordx4 v[126:129], v247, s[14:15] offset:176
	global_load_dwordx4 v[130:133], v247, s[14:15] offset:192
	global_load_dwordx4 v[134:137], v247, s[14:15] offset:208
	global_load_dwordx4 v[138:141], v247, s[14:15] offset:224
	global_load_dwordx4 v[142:145], v247, s[14:15] offset:240
	s_add_u32 s14, s14, 0x400000
	s_addc_u32 s15, s15, 0
	global_load_dwordx4 v[64:67], v247, s[14:15]
	global_load_dwordx4 v[68:71], v247, s[14:15] offset:16
	global_load_dwordx4 v[72:75], v247, s[14:15] offset:32
	global_load_dwordx4 v[76:79], v247, s[14:15] offset:48
	global_load_dwordx4 v[152:155], v247, s[14:15] offset:64
	global_load_dwordx4 v[156:159], v247, s[14:15] offset:80
	global_load_dwordx4 v[160:163], v247, s[14:15] offset:96
	global_load_dwordx4 v[170:173], v247, s[14:15] offset:112
	global_load_dwordx4 v[174:177], v247, s[14:15] offset:128
	global_load_dwordx4 v[178:181], v247, s[14:15] offset:144
	global_load_dwordx4 v[182:185], v247, s[14:15] offset:160
	global_load_dwordx4 v[220:223], v247, s[14:15] offset:176
	global_load_dwordx4 v[224:227], v247, s[14:15] offset:192
	global_load_dwordx4 v[228:231], v247, s[14:15] offset:208
	global_load_dwordx4 v[232:235], v247, s[14:15] offset:224
	global_load_dwordx4 v[236:239], v247, s[14:15] offset:240
	s_add_u32 s14, s14, 0x400000
	s_addc_u32 s15, s15, 0
	s_waitcnt vmcnt(0)
	v_pk_add_f32 v[0:1], v[0:1], v[82:83]
	v_pk_add_f32 v[2:3], v[2:3], v[84:85]
	v_pk_add_f32 v[4:5], v[4:5], v[86:87]
	v_pk_add_f32 v[6:7], v[6:7], v[88:89]
	v_pk_add_f32 v[8:9], v[8:9], v[90:91]
	v_pk_add_f32 v[10:11], v[10:11], v[92:93]
	v_pk_add_f32 v[12:13], v[12:13], v[94:95]
	v_pk_add_f32 v[14:15], v[14:15], v[96:97]
	v_pk_add_f32 v[16:17], v[16:17], v[98:99]
	v_pk_add_f32 v[18:19], v[18:19], v[100:101]
	v_pk_add_f32 v[20:21], v[20:21], v[102:103]
	v_pk_add_f32 v[22:23], v[22:23], v[104:105]
	v_pk_add_f32 v[24:25], v[24:25], v[106:107]
	v_pk_add_f32 v[26:27], v[26:27], v[108:109]
	v_pk_add_f32 v[28:29], v[28:29], v[110:111]
	v_pk_add_f32 v[30:31], v[30:31], v[112:113]
	v_pk_add_f32 v[32:33], v[32:33], v[114:115]
	v_pk_add_f32 v[34:35], v[34:35], v[116:117]
	v_pk_add_f32 v[36:37], v[36:37], v[118:119]
	v_pk_add_f32 v[38:39], v[38:39], v[120:121]
	v_pk_add_f32 v[40:41], v[40:41], v[122:123]
	v_pk_add_f32 v[42:43], v[42:43], v[124:125]
	v_pk_add_f32 v[44:45], v[44:45], v[126:127]
	v_pk_add_f32 v[46:47], v[46:47], v[128:129]
	v_pk_add_f32 v[48:49], v[48:49], v[130:131]
	v_pk_add_f32 v[50:51], v[50:51], v[132:133]
	v_pk_add_f32 v[52:53], v[52:53], v[134:135]
	v_pk_add_f32 v[54:55], v[54:55], v[136:137]
	v_pk_add_f32 v[56:57], v[56:57], v[138:139]
	v_pk_add_f32 v[58:59], v[58:59], v[140:141]
	v_pk_add_f32 v[60:61], v[60:61], v[142:143]
	v_pk_add_f32 v[62:63], v[62:63], v[144:145]
; __global__ void __launch_bounds__(512, 2) hybrid_fwd(Params P) {
;     ...
;                 f32x4 hv = *(const f32x4*)((const float*)(ws + WS_SMALL) + kv * 256 + 4 * lane);
;                 { const float* pp = (const float*)(ws + WS_H) + ((size_t)(kv * 4) * 4096 + rr) * 256 + 4 * lane;
; #pragma unroll
;                     for (int ks = 0; ks < 4; ++ks) hv += *(const f32x4*)(pp + (size_t)ks * 4096 * 256);
	v_pk_add_f32 v[0:1], v[0:1], v[64:65]
	v_pk_add_f32 v[2:3], v[2:3], v[66:67]
	v_pk_add_f32 v[4:5], v[4:5], v[68:69]
	v_pk_add_f32 v[6:7], v[6:7], v[70:71]
	v_pk_add_f32 v[8:9], v[8:9], v[72:73]
	v_pk_add_f32 v[10:11], v[10:11], v[74:75]
	v_pk_add_f32 v[12:13], v[12:13], v[76:77]
	v_pk_add_f32 v[14:15], v[14:15], v[78:79]
	v_pk_add_f32 v[16:17], v[16:17], v[152:153]
	v_pk_add_f32 v[18:19], v[18:19], v[154:155]
	v_pk_add_f32 v[20:21], v[20:21], v[156:157]
	v_pk_add_f32 v[22:23], v[22:23], v[158:159]
	v_pk_add_f32 v[24:25], v[24:25], v[160:161]
	v_pk_add_f32 v[26:27], v[26:27], v[162:163]
	v_pk_add_f32 v[28:29], v[28:29], v[170:171]
	v_pk_add_f32 v[30:31], v[30:31], v[172:173]
	v_pk_add_f32 v[32:33], v[32:33], v[174:175]
	v_pk_add_f32 v[34:35], v[34:35], v[176:177]
	v_pk_add_f32 v[36:37], v[36:37], v[178:179]
	v_pk_add_f32 v[38:39], v[38:39], v[180:181]
	v_pk_add_f32 v[40:41], v[40:41], v[182:183]
	v_pk_add_f32 v[42:43], v[42:43], v[184:185]
	v_pk_add_f32 v[44:45], v[44:45], v[220:221]
	v_pk_add_f32 v[46:47], v[46:47], v[222:223]
	v_pk_add_f32 v[48:49], v[48:49], v[224:225]
	v_pk_add_f32 v[50:51], v[50:51], v[226:227]
	v_pk_add_f32 v[52:53], v[52:53], v[228:229]
	v_pk_add_f32 v[54:55], v[54:55], v[230:231]
	v_pk_add_f32 v[56:57], v[56:57], v[232:233]
	v_pk_add_f32 v[58:59], v[58:59], v[234:235]
	v_pk_add_f32 v[60:61], v[60:61], v[236:237]
	v_pk_add_f32 v[62:63], v[62:63], v[238:239]
	global_load_dwordx4 v[82:85], v247, s[14:15]
	global_load_dwordx4 v[86:89], v247, s[14:15] offset:16
	global_load_dwordx4 v[90:93], v247, s[14:15] offset:32
	global_load_dwordx4 v[94:97], v247, s[14:15] offset:48
	global_load_dwordx4 v[98:101], v247, s[14:15] offset:64
	global_load_dwordx4 v[102:105], v247, s[14:15] offset:80
	global_load_dwordx4 v[106:109], v247, s[14:15] offset:96
	global_load_dwordx4 v[110:113], v247, s[14:15] offset:112
	global_load_dwordx4 v[114:117], v247, s[14:15] offset:128
	global_load_dwordx4 v[118:121], v247, s[14:15] offset:144
	global_load_dwordx4 v[122:125], v247, s[14:15] offset:160
	global_load_dwordx4 v[126:129], v247, s[14:15] offset:176
	global_load_dwordx4 v[130:133], v247, s[14:15] offset:192
	global_load_dwordx4 v[134:137], v247, s[14:15] offset:208
	global_load_dwordx4 v[138:141], v247, s[14:15] offset:224
	global_load_dwordx4 v[142:145], v247, s[14:15] offset:240
	s_add_u32 s14, s14, 0x400000
	s_addc_u32 s15, s15, 0
	global_load_dwordx4 v[64:67], v247, s[14:15]
	global_load_dwordx4 v[68:71], v247, s[14:15] offset:16
	global_load_dwordx4 v[72:75], v247, s[14:15] offset:32
	global_load_dwordx4 v[76:79], v247, s[14:15] offset:48
	global_load_dwordx4 v[152:155], v247, s[14:15] offset:64
	global_load_dwordx4 v[156:159], v247, s[14:15] offset:80
	global_load_dwordx4 v[160:163], v247, s[14:15] offset:96
	global_load_dwordx4 v[170:173], v247, s[14:15] offset:112
	global_load_dwordx4 v[174:177], v247, s[14:15] offset:128
	global_load_dwordx4 v[178:181], v247, s[14:15] offset:144
	global_load_dwordx4 v[182:185], v247, s[14:15] offset:160
	global_load_dwordx4 v[220:223], v247, s[14:15] offset:176
	global_load_dwordx4 v[224:227], v247, s[14:15] offset:192
	global_load_dwordx4 v[228:231], v247, s[14:15] offset:208
	global_load_dwordx4 v[232:235], v247, s[14:15] offset:224
	global_load_dwordx4 v[236:239], v247, s[14:15] offset:240
	s_waitcnt vmcnt(0)
	v_pk_add_f32 v[0:1], v[0:1], v[82:83]
	v_pk_add_f32 v[2:3], v[2:3], v[84:85]
	v_pk_add_f32 v[4:5], v[4:5], v[86:87]
	v_pk_add_f32 v[6:7], v[6:7], v[88:89]
	v_pk_add_f32 v[8:9], v[8:9], v[90:91]
	v_pk_add_f32 v[10:11], v[10:11], v[92:93]
	v_pk_add_f32 v[12:13], v[12:13], v[94:95]
	v_pk_add_f32 v[14:15], v[14:15], v[96:97]
	v_pk_add_f32 v[16:17], v[16:17], v[98:99]
	v_pk_add_f32 v[18:19], v[18:19], v[100:101]
	v_pk_add_f32 v[20:21], v[20:21], v[102:103]
	v_pk_add_f32 v[22:23], v[22:23], v[104:105]
	v_pk_add_f32 v[24:25], v[24:25], v[106:107]
	v_pk_add_f32 v[26:27], v[26:27], v[108:109]
	v_pk_add_f32 v[28:29], v[28:29], v[110:111]
	v_pk_add_f32 v[30:31], v[30:31], v[112:113]
	v_pk_add_f32 v[32:33], v[32:33], v[114:115]
	v_pk_add_f32 v[34:35], v[34:35], v[116:117]
	v_pk_add_f32 v[36:37], v[36:37], v[118:119]
	v_pk_add_f32 v[38:39], v[38:39], v[120:121]
	v_pk_add_f32 v[40:41], v[40:41], v[122:123]
	v_pk_add_f32 v[42:43], v[42:43], v[124:125]
	v_pk_add_f32 v[44:45], v[44:45], v[126:127]
	v_pk_add_f32 v[46:47], v[46:47], v[128:129]
	v_pk_add_f32 v[48:49], v[48:49], v[130:131]
	v_pk_add_f32 v[50:51], v[50:51], v[132:133]
	v_pk_add_f32 v[52:53], v[52:53], v[134:135]
	v_pk_add_f32 v[54:55], v[54:55], v[136:137]
	v_pk_add_f32 v[56:57], v[56:57], v[138:139]
	v_pk_add_f32 v[58:59], v[58:59], v[140:141]
	v_pk_add_f32 v[60:61], v[60:61], v[142:143]
	v_pk_add_f32 v[62:63], v[62:63], v[144:145]
	v_pk_add_f32 v[0:1], v[0:1], v[64:65]
	v_pk_add_f32 v[2:3], v[2:3], v[66:67]
	v_pk_add_f32 v[4:5], v[4:5], v[68:69]
	v_pk_add_f32 v[6:7], v[6:7], v[70:71]
	v_pk_add_f32 v[8:9], v[8:9], v[72:73]
	v_pk_add_f32 v[10:11], v[10:11], v[74:75]
	v_pk_add_f32 v[12:13], v[12:13], v[76:77]
	v_pk_add_f32 v[14:15], v[14:15], v[78:79]
	v_pk_add_f32 v[16:17], v[16:17], v[152:153]
	v_pk_add_f32 v[18:19], v[18:19], v[154:155]
	v_pk_add_f32 v[20:21], v[20:21], v[156:157]
	v_pk_add_f32 v[22:23], v[22:23], v[158:159]
	v_pk_add_f32 v[24:25], v[24:25], v[160:161]
	v_pk_add_f32 v[26:27], v[26:27], v[162:163]
	v_pk_add_f32 v[28:29], v[28:29], v[170:171]
	v_pk_add_f32 v[30:31], v[30:31], v[172:173]
	v_pk_add_f32 v[32:33], v[32:33], v[174:175]
	v_pk_add_f32 v[34:35], v[34:35], v[176:177]
	v_pk_add_f32 v[36:37], v[36:37], v[178:179]
	v_pk_add_f32 v[38:39], v[38:39], v[180:181]
	v_pk_add_f32 v[40:41], v[40:41], v[182:183]
; __global__ void __launch_bounds__(512, 2) hybrid_fwd(Params P) {
;     ...
;                     for (int e = 0; e < 4; ++e) { const float t = hv[e], z = 0.7978845608028654f * (t + 0.044715f * t * t * t);
;                         const float th = 1.0f - 2.0f * __builtin_amdgcn_rcpf(1.0f + __expf(2.0f * z)); hv[e] = 0.5f * t * (1.0f + th); } }
;                 const float* wp = cw2 + (size_t)kv * 256 * 64 + lane; float a = 0.f;
; #pragma unroll
;                 for (int k = 0; k < 256; ++k) { const float hk = __uint_as_float(__builtin_amdgcn_readlane(__float_as_uint(hv[k & 3]), k >> 2)); a = fmaf(hk, wp[k * 64], a); }
	v_pk_add_f32 v[42:43], v[42:43], v[184:185]
	v_pk_add_f32 v[44:45], v[44:45], v[220:221]
	v_pk_add_f32 v[46:47], v[46:47], v[222:223]
	v_pk_add_f32 v[48:49], v[48:49], v[224:225]
	v_pk_add_f32 v[50:51], v[50:51], v[226:227]
	v_pk_add_f32 v[52:53], v[52:53], v[228:229]
	v_pk_add_f32 v[54:55], v[54:55], v[230:231]
	v_pk_add_f32 v[56:57], v[56:57], v[232:233]
	v_pk_add_f32 v[58:59], v[58:59], v[234:235]
	v_pk_add_f32 v[60:61], v[60:61], v[236:237]
	v_pk_add_f32 v[62:63], v[62:63], v[238:239]
	global_load_dwordx4 v[82:85], v249, s[10:11]
	global_load_dwordx4 v[86:89], v249, s[10:11] offset:256
	global_load_dwordx4 v[90:93], v249, s[10:11] offset:512
	global_load_dwordx4 v[94:97], v249, s[10:11] offset:768
	global_load_dwordx4 v[98:101], v249, s[10:11] offset:1024
	global_load_dwordx4 v[102:105], v249, s[10:11] offset:1280
	global_load_dwordx4 v[106:109], v249, s[10:11] offset:1536
	global_load_dwordx4 v[110:113], v249, s[10:11] offset:1792
	s_add_u32 s10, s10, 0x800
	s_addc_u32 s11, s11, 0
	global_load_dwordx4 v[114:117], v249, s[10:11]
	global_load_dwordx4 v[118:121], v249, s[10:11] offset:256
	global_load_dwordx4 v[122:125], v249, s[10:11] offset:512
	global_load_dwordx4 v[126:129], v249, s[10:11] offset:768
	global_load_dwordx4 v[130:133], v249, s[10:11] offset:1024
	global_load_dwordx4 v[134:137], v249, s[10:11] offset:1280
	global_load_dwordx4 v[138:141], v249, s[10:11] offset:1536
	global_load_dwordx4 v[142:145], v249, s[10:11] offset:1792
	s_add_u32 s10, s10, 0x800
	s_addc_u32 s11, s11, 0
	s_mov_b32 s16, 0x3d372713
	s_mov_b32 s18, 0x40135761
	v_mul_f32_e32 v224, v0, v0
	v_mul_f32_e32 v224, v224, v0
	v_fma_f32 v225, s16, v224, v0
	v_mul_f32_e32 v225, s18, v225
	v_exp_f32_e32 v226, v225
	v_mul_f32_e32 v227, 0.5, v0
	s_nop 0
	v_add_f32_e32 v226, 1.0, v226
	v_rcp_f32_e32 v226, v226
	s_nop 0
	v_fma_f32 v226, v226, -2.0, 1.0
	v_fma_f32 v0, v227, v226, v227
	v_mul_f32_e32 v224, v1, v1
	v_mul_f32_e32 v224, v224, v1
	v_fma_f32 v225, s16, v224, v1
	v_mul_f32_e32 v225, s18, v225
	v_exp_f32_e32 v226, v225
	v_mul_f32_e32 v227, 0.5, v1
	s_nop 0
	v_add_f32_e32 v226, 1.0, v226
	v_rcp_f32_e32 v226, v226
	s_nop 0
	v_fma_f32 v226, v226, -2.0, 1.0
	v_fma_f32 v1, v227, v226, v227
	v_mul_f32_e32 v224, v2, v2
	v_mul_f32_e32 v224, v224, v2
	v_fma_f32 v225, s16, v224, v2
	v_mul_f32_e32 v225, s18, v225
	v_exp_f32_e32 v226, v225
	v_mul_f32_e32 v227, 0.5, v2
	s_nop 0
	v_add_f32_e32 v226, 1.0, v226
	v_rcp_f32_e32 v226, v226
	s_nop 0
	v_fma_f32 v226, v226, -2.0, 1.0
	v_fma_f32 v2, v227, v226, v227
	v_mul_f32_e32 v224, v3, v3
	v_mul_f32_e32 v224, v224, v3
	v_fma_f32 v225, s16, v224, v3
	v_mul_f32_e32 v225, s18, v225
	v_exp_f32_e32 v226, v225
	v_mul_f32_e32 v227, 0.5, v3
	s_nop 0
	v_add_f32_e32 v226, 1.0, v226
	v_rcp_f32_e32 v226, v226
	s_nop 0
	v_fma_f32 v226, v226, -2.0, 1.0
	v_fma_f32 v3, v227, v226, v227
	v_mul_f32_e32 v224, v4, v4
	v_mul_f32_e32 v224, v224, v4
	v_fma_f32 v225, s16, v224, v4
	v_mul_f32_e32 v225, s18, v225
	v_exp_f32_e32 v226, v225
	v_mul_f32_e32 v227, 0.5, v4
	s_nop 0
	v_add_f32_e32 v226, 1.0, v226
	v_rcp_f32_e32 v226, v226
	s_nop 0
	v_fma_f32 v226, v226, -2.0, 1.0
	v_fma_f32 v4, v227, v226, v227
	v_mul_f32_e32 v224, v5, v5
	v_mul_f32_e32 v224, v224, v5
	v_fma_f32 v225, s16, v224, v5
	v_mul_f32_e32 v225, s18, v225
	v_exp_f32_e32 v226, v225
	v_mul_f32_e32 v227, 0.5, v5
	s_nop 0
	v_add_f32_e32 v226, 1.0, v226
	v_rcp_f32_e32 v226, v226
	s_nop 0
	v_fma_f32 v226, v226, -2.0, 1.0
	v_fma_f32 v5, v227, v226, v227
	v_mul_f32_e32 v224, v6, v6
	v_mul_f32_e32 v224, v224, v6
	v_fma_f32 v225, s16, v224, v6
	v_mul_f32_e32 v225, s18, v225
	v_exp_f32_e32 v226, v225
	v_mul_f32_e32 v227, 0.5, v6
	s_nop 0
	v_add_f32_e32 v226, 1.0, v226
	v_rcp_f32_e32 v226, v226
	s_nop 0
	v_fma_f32 v226, v226, -2.0, 1.0
	v_fma_f32 v6, v227, v226, v227
	v_mul_f32_e32 v224, v7, v7
	v_mul_f32_e32 v224, v224, v7
	v_fma_f32 v225, s16, v224, v7
	v_mul_f32_e32 v225, s18, v225
	v_exp_f32_e32 v226, v225
	v_mul_f32_e32 v227, 0.5, v7
	s_nop 0
	v_add_f32_e32 v226, 1.0, v226
	v_rcp_f32_e32 v226, v226
	s_nop 0
	v_fma_f32 v226, v226, -2.0, 1.0
	v_fma_f32 v7, v227, v226, v227
	v_mov_b32_e32 v64, 0
	v_mov_b32_e32 v65, 0
	v_mov_b32_e32 v66, 0
	v_mov_b32_e32 v67, 0
	v_mov_b32_e32 v68, 0
	v_mov_b32_e32 v69, 0
	v_mov_b32_e32 v70, 0
	v_mov_b32_e32 v71, 0
	v_mov_b32_e32 v72, 0
	v_mov_b32_e32 v73, 0
	v_mov_b32_e32 v74, 0
	v_mov_b32_e32 v75, 0
	v_mov_b32_e32 v76, 0
	v_mov_b32_e32 v77, 0
	v_mov_b32_e32 v78, 0
	v_mov_b32_e32 v79, 0
	global_load_dwordx4 v[152:155], v249, s[10:11]
	global_load_dwordx4 v[156:159], v249, s[10:11] offset:256
	global_load_dwordx4 v[160:163], v249, s[10:11] offset:512
	global_load_dwordx4 v[170:173], v249, s[10:11] offset:768
	global_load_dwordx4 v[174:177], v249, s[10:11] offset:1024
	global_load_dwordx4 v[178:181], v249, s[10:11] offset:1280
	global_load_dwordx4 v[182:185], v249, s[10:11] offset:1536
	global_load_dwordx4 v[220:223], v249, s[10:11] offset:1792
	s_add_u32 s10, s10, 0x800
	s_addc_u32 s11, s11, 0
	s_waitcnt vmcnt(16)
; __global__ void __launch_bounds__(512, 2) hybrid_fwd(Params P) {
;     ...
;                     for (int e = 0; e < 4; ++e) { const float t = hv[e], z = 0.7978845608028654f * (t + 0.044715f * t * t * t);
;                         const float th = 1.0f - 2.0f * __builtin_amdgcn_rcpf(1.0f + __expf(2.0f * z)); hv[e] = 0.5f * t * (1.0f + th); } }
;                 const float* wp = cw2 + (size_t)kv * 256 * 64 + lane; float a = 0.f;
; #pragma unroll
;                 for (int k = 0; k < 256; ++k) { const float hk = __uint_as_float(__builtin_amdgcn_readlane(__float_as_uint(hv[k & 3]), k >> 2)); a = fmaf(hk, wp[k * 64], a); }
	v_mfma_f32_16x16x4_f32 v[64:67], v0, v82, v[64:67]
	v_mul_f32_e32 v224, v8, v8
	v_mul_f32_e32 v224, v224, v8
	v_fma_f32 v225, s16, v224, v8
	v_mfma_f32_16x16x4_f32 v[68:71], v0, v83, v[68:71]
	v_mul_f32_e32 v225, s18, v225
	v_exp_f32_e32 v226, v225
	v_mul_f32_e32 v227, 0.5, v8
	v_mfma_f32_16x16x4_f32 v[72:75], v0, v84, v[72:75]
	v_add_f32_e32 v226, 1.0, v226
	v_rcp_f32_e32 v226, v226
	v_mfma_f32_16x16x4_f32 v[76:79], v0, v85, v[76:79]
	v_fma_f32 v226, v226, -2.0, 1.0
	v_fma_f32 v8, v227, v226, v227
	v_mfma_f32_16x16x4_f32 v[64:67], v1, v86, v[64:67]
	v_mul_f32_e32 v224, v9, v9
	v_mul_f32_e32 v224, v224, v9
	v_fma_f32 v225, s16, v224, v9
	v_mfma_f32_16x16x4_f32 v[68:71], v1, v87, v[68:71]
	v_mul_f32_e32 v225, s18, v225
	v_exp_f32_e32 v226, v225
	v_mul_f32_e32 v227, 0.5, v9
	v_mfma_f32_16x16x4_f32 v[72:75], v1, v88, v[72:75]
	v_add_f32_e32 v226, 1.0, v226
	v_rcp_f32_e32 v226, v226
	v_mfma_f32_16x16x4_f32 v[76:79], v1, v89, v[76:79]
	v_fma_f32 v226, v226, -2.0, 1.0
	v_fma_f32 v9, v227, v226, v227
	v_mfma_f32_16x16x4_f32 v[64:67], v2, v90, v[64:67]
	v_mul_f32_e32 v224, v10, v10
	v_mul_f32_e32 v224, v224, v10
	v_fma_f32 v225, s16, v224, v10
	v_mfma_f32_16x16x4_f32 v[68:71], v2, v91, v[68:71]
	v_mul_f32_e32 v225, s18, v225
	v_exp_f32_e32 v226, v225
	v_mul_f32_e32 v227, 0.5, v10
	v_mfma_f32_16x16x4_f32 v[72:75], v2, v92, v[72:75]
	v_add_f32_e32 v226, 1.0, v226
	v_rcp_f32_e32 v226, v226
	v_mfma_f32_16x16x4_f32 v[76:79], v2, v93, v[76:79]
	v_fma_f32 v226, v226, -2.0, 1.0
	v_fma_f32 v10, v227, v226, v227
	v_mfma_f32_16x16x4_f32 v[64:67], v3, v94, v[64:67]
	v_mul_f32_e32 v224, v11, v11
	v_mul_f32_e32 v224, v224, v11
	v_fma_f32 v225, s16, v224, v11
	v_mfma_f32_16x16x4_f32 v[68:71], v3, v95, v[68:71]
	v_mul_f32_e32 v225, s18, v225
	v_exp_f32_e32 v226, v225
	v_mul_f32_e32 v227, 0.5, v11
	v_mfma_f32_16x16x4_f32 v[72:75], v3, v96, v[72:75]
	v_add_f32_e32 v226, 1.0, v226
	v_rcp_f32_e32 v226, v226
	v_mfma_f32_16x16x4_f32 v[76:79], v3, v97, v[76:79]
	v_fma_f32 v226, v226, -2.0, 1.0
	v_fma_f32 v11, v227, v226, v227
	v_mfma_f32_16x16x4_f32 v[64:67], v4, v98, v[64:67]
	v_mul_f32_e32 v224, v12, v12
	v_mul_f32_e32 v224, v224, v12
	v_fma_f32 v225, s16, v224, v12
	v_mfma_f32_16x16x4_f32 v[68:71], v4, v99, v[68:71]
	v_mul_f32_e32 v225, s18, v225
	v_exp_f32_e32 v226, v225
	v_mul_f32_e32 v227, 0.5, v12
	v_mfma_f32_16x16x4_f32 v[72:75], v4, v100, v[72:75]
	v_add_f32_e32 v226, 1.0, v226
	v_rcp_f32_e32 v226, v226
	v_mfma_f32_16x16x4_f32 v[76:79], v4, v101, v[76:79]
	v_fma_f32 v226, v226, -2.0, 1.0
	v_fma_f32 v12, v227, v226, v227
	v_mfma_f32_16x16x4_f32 v[64:67], v5, v102, v[64:67]
	v_mul_f32_e32 v224, v13, v13
	v_mul_f32_e32 v224, v224, v13
	v_fma_f32 v225, s16, v224, v13
	v_mfma_f32_16x16x4_f32 v[68:71], v5, v103, v[68:71]
	v_mul_f32_e32 v225, s18, v225
	v_exp_f32_e32 v226, v225
	v_mul_f32_e32 v227, 0.5, v13
	v_mfma_f32_16x16x4_f32 v[72:75], v5, v104, v[72:75]
	v_add_f32_e32 v226, 1.0, v226
	v_rcp_f32_e32 v226, v226
	v_mfma_f32_16x16x4_f32 v[76:79], v5, v105, v[76:79]
	v_fma_f32 v226, v226, -2.0, 1.0
	v_fma_f32 v13, v227, v226, v227
	v_mfma_f32_16x16x4_f32 v[64:67], v6, v106, v[64:67]
	v_mul_f32_e32 v224, v14, v14
	v_mul_f32_e32 v224, v224, v14
	v_fma_f32 v225, s16, v224, v14
	v_mfma_f32_16x16x4_f32 v[68:71], v6, v107, v[68:71]
	v_mul_f32_e32 v225, s18, v225
	v_exp_f32_e32 v226, v225
	v_mul_f32_e32 v227, 0.5, v14
	v_mfma_f32_16x16x4_f32 v[72:75], v6, v108, v[72:75]
	v_add_f32_e32 v226, 1.0, v226
	v_rcp_f32_e32 v226, v226
	v_mfma_f32_16x16x4_f32 v[76:79], v6, v109, v[76:79]
	v_fma_f32 v226, v226, -2.0, 1.0
	v_fma_f32 v14, v227, v226, v227
	v_mfma_f32_16x16x4_f32 v[64:67], v7, v110, v[64:67]
	v_mul_f32_e32 v224, v15, v15
	v_mul_f32_e32 v224, v224, v15
	v_fma_f32 v225, s16, v224, v15
	v_mfma_f32_16x16x4_f32 v[68:71], v7, v111, v[68:71]
	v_mul_f32_e32 v225, s18, v225
	v_exp_f32_e32 v226, v225
	v_mul_f32_e32 v227, 0.5, v15
	v_mfma_f32_16x16x4_f32 v[72:75], v7, v112, v[72:75]
	v_add_f32_e32 v226, 1.0, v226
	v_rcp_f32_e32 v226, v226
	v_mfma_f32_16x16x4_f32 v[76:79], v7, v113, v[76:79]
	v_fma_f32 v226, v226, -2.0, 1.0
	v_fma_f32 v15, v227, v226, v227
	global_load_dwordx4 v[82:85], v249, s[10:11]
	global_load_dwordx4 v[86:89], v249, s[10:11] offset:256
	global_load_dwordx4 v[90:93], v249, s[10:11] offset:512
	global_load_dwordx4 v[94:97], v249, s[10:11] offset:768
	global_load_dwordx4 v[98:101], v249, s[10:11] offset:1024
	global_load_dwordx4 v[102:105], v249, s[10:11] offset:1280
	global_load_dwordx4 v[106:109], v249, s[10:11] offset:1536
	global_load_dwordx4 v[110:113], v249, s[10:11] offset:1792
	s_add_u32 s10, s10, 0x800
	s_addc_u32 s11, s11, 0
	s_waitcnt vmcnt(16)
; __global__ void __launch_bounds__(512, 2) hybrid_fwd(Params P) {
;     ...
;                     for (int e = 0; e < 4; ++e) { const float t = hv[e], z = 0.7978845608028654f * (t + 0.044715f * t * t * t);
;                         const float th = 1.0f - 2.0f * __builtin_amdgcn_rcpf(1.0f + __expf(2.0f * z)); hv[e] = 0.5f * t * (1.0f + th); } }
;                 const float* wp = cw2 + (size_t)kv * 256 * 64 + lane; float a = 0.f;
; #pragma unroll
;                 for (int k = 0; k < 256; ++k) { const float hk = __uint_as_float(__builtin_amdgcn_readlane(__float_as_uint(hv[k & 3]), k >> 2)); a = fmaf(hk, wp[k * 64], a); }
	v_mfma_f32_16x16x4_f32 v[64:67], v8, v114, v[64:67]
	v_mul_f32_e32 v224, v16, v16
	v_mul_f32_e32 v224, v224, v16
	v_fma_f32 v225, s16, v224, v16
	v_mfma_f32_16x16x4_f32 v[68:71], v8, v115, v[68:71]
	v_mul_f32_e32 v225, s18, v225
	v_exp_f32_e32 v226, v225
	v_mul_f32_e32 v227, 0.5, v16
	v_mfma_f32_16x16x4_f32 v[72:75], v8, v116, v[72:75]
	v_add_f32_e32 v226, 1.0, v226
	v_rcp_f32_e32 v226, v226
	v_mfma_f32_16x16x4_f32 v[76:79], v8, v117, v[76:79]
	v_fma_f32 v226, v226, -2.0, 1.0
	v_fma_f32 v16, v227, v226, v227
	v_mfma_f32_16x16x4_f32 v[64:67], v9, v118, v[64:67]
	v_mul_f32_e32 v224, v17, v17
	v_mul_f32_e32 v224, v224, v17
	v_fma_f32 v225, s16, v224, v17
	v_mfma_f32_16x16x4_f32 v[68:71], v9, v119, v[68:71]
	v_mul_f32_e32 v225, s18, v225
	v_exp_f32_e32 v226, v225
	v_mul_f32_e32 v227, 0.5, v17
	v_mfma_f32_16x16x4_f32 v[72:75], v9, v120, v[72:75]
	v_add_f32_e32 v226, 1.0, v226
	v_rcp_f32_e32 v226, v226
	v_mfma_f32_16x16x4_f32 v[76:79], v9, v121, v[76:79]
	v_fma_f32 v226, v226, -2.0, 1.0
	v_fma_f32 v17, v227, v226, v227
	v_mfma_f32_16x16x4_f32 v[64:67], v10, v122, v[64:67]
	v_mul_f32_e32 v224, v18, v18
	v_mul_f32_e32 v224, v224, v18
	v_fma_f32 v225, s16, v224, v18
	v_mfma_f32_16x16x4_f32 v[68:71], v10, v123, v[68:71]
	v_mul_f32_e32 v225, s18, v225
	v_exp_f32_e32 v226, v225
	v_mul_f32_e32 v227, 0.5, v18
	v_mfma_f32_16x16x4_f32 v[72:75], v10, v124, v[72:75]
	v_add_f32_e32 v226, 1.0, v226
	v_rcp_f32_e32 v226, v226
	v_mfma_f32_16x16x4_f32 v[76:79], v10, v125, v[76:79]
	v_fma_f32 v226, v226, -2.0, 1.0
	v_fma_f32 v18, v227, v226, v227
	v_mfma_f32_16x16x4_f32 v[64:67], v11, v126, v[64:67]
	v_mul_f32_e32 v224, v19, v19
	v_mul_f32_e32 v224, v224, v19
	v_fma_f32 v225, s16, v224, v19
	v_mfma_f32_16x16x4_f32 v[68:71], v11, v127, v[68:71]
	v_mul_f32_e32 v225, s18, v225
	v_exp_f32_e32 v226, v225
	v_mul_f32_e32 v227, 0.5, v19
	v_mfma_f32_16x16x4_f32 v[72:75], v11, v128, v[72:75]
	v_add_f32_e32 v226, 1.0, v226
	v_rcp_f32_e32 v226, v226
	v_mfma_f32_16x16x4_f32 v[76:79], v11, v129, v[76:79]
	v_fma_f32 v226, v226, -2.0, 1.0
	v_fma_f32 v19, v227, v226, v227
	v_mfma_f32_16x16x4_f32 v[64:67], v12, v130, v[64:67]
	v_mul_f32_e32 v224, v20, v20
	v_mul_f32_e32 v224, v224, v20
	v_fma_f32 v225, s16, v224, v20
	v_mfma_f32_16x16x4_f32 v[68:71], v12, v131, v[68:71]
	v_mul_f32_e32 v225, s18, v225
	v_exp_f32_e32 v226, v225
	v_mul_f32_e32 v227, 0.5, v20
	v_mfma_f32_16x16x4_f32 v[72:75], v12, v132, v[72:75]
	v_add_f32_e32 v226, 1.0, v226
	v_rcp_f32_e32 v226, v226
	v_mfma_f32_16x16x4_f32 v[76:79], v12, v133, v[76:79]
	v_fma_f32 v226, v226, -2.0, 1.0
	v_fma_f32 v20, v227, v226, v227
	v_mfma_f32_16x16x4_f32 v[64:67], v13, v134, v[64:67]
	v_mul_f32_e32 v224, v21, v21
	v_mul_f32_e32 v224, v224, v21
	v_fma_f32 v225, s16, v224, v21
	v_mfma_f32_16x16x4_f32 v[68:71], v13, v135, v[68:71]
	v_mul_f32_e32 v225, s18, v225
	v_exp_f32_e32 v226, v225
	v_mul_f32_e32 v227, 0.5, v21
	v_mfma_f32_16x16x4_f32 v[72:75], v13, v136, v[72:75]
	v_add_f32_e32 v226, 1.0, v226
	v_rcp_f32_e32 v226, v226
	v_mfma_f32_16x16x4_f32 v[76:79], v13, v137, v[76:79]
	v_fma_f32 v226, v226, -2.0, 1.0
	v_fma_f32 v21, v227, v226, v227
	v_mfma_f32_16x16x4_f32 v[64:67], v14, v138, v[64:67]
	v_mul_f32_e32 v224, v22, v22
	v_mul_f32_e32 v224, v224, v22
	v_fma_f32 v225, s16, v224, v22
	v_mfma_f32_16x16x4_f32 v[68:71], v14, v139, v[68:71]
	v_mul_f32_e32 v225, s18, v225
	v_exp_f32_e32 v226, v225
	v_mul_f32_e32 v227, 0.5, v22
	v_mfma_f32_16x16x4_f32 v[72:75], v14, v140, v[72:75]
	v_add_f32_e32 v226, 1.0, v226
	v_rcp_f32_e32 v226, v226
	v_mfma_f32_16x16x4_f32 v[76:79], v14, v141, v[76:79]
	v_fma_f32 v226, v226, -2.0, 1.0
	v_fma_f32 v22, v227, v226, v227
	v_mfma_f32_16x16x4_f32 v[64:67], v15, v142, v[64:67]
	v_mul_f32_e32 v224, v23, v23
	v_mul_f32_e32 v224, v224, v23
	v_fma_f32 v225, s16, v224, v23
	v_mfma_f32_16x16x4_f32 v[68:71], v15, v143, v[68:71]
	v_mul_f32_e32 v225, s18, v225
	v_exp_f32_e32 v226, v225
	v_mul_f32_e32 v227, 0.5, v23
	v_mfma_f32_16x16x4_f32 v[72:75], v15, v144, v[72:75]
	v_add_f32_e32 v226, 1.0, v226
	v_rcp_f32_e32 v226, v226
	v_mfma_f32_16x16x4_f32 v[76:79], v15, v145, v[76:79]
	v_fma_f32 v226, v226, -2.0, 1.0
	v_fma_f32 v23, v227, v226, v227
	global_load_dwordx4 v[114:117], v249, s[10:11]
	global_load_dwordx4 v[118:121], v249, s[10:11] offset:256
	global_load_dwordx4 v[122:125], v249, s[10:11] offset:512
	global_load_dwordx4 v[126:129], v249, s[10:11] offset:768
	global_load_dwordx4 v[130:133], v249, s[10:11] offset:1024
	global_load_dwordx4 v[134:137], v249, s[10:11] offset:1280
	global_load_dwordx4 v[138:141], v249, s[10:11] offset:1536
	global_load_dwordx4 v[142:145], v249, s[10:11] offset:1792
	s_add_u32 s10, s10, 0x800
	s_addc_u32 s11, s11, 0
	s_waitcnt vmcnt(16)
; __global__ void __launch_bounds__(512, 2) hybrid_fwd(Params P) {
;     ...
;                     for (int e = 0; e < 4; ++e) { const float t = hv[e], z = 0.7978845608028654f * (t + 0.044715f * t * t * t);
;                         const float th = 1.0f - 2.0f * __builtin_amdgcn_rcpf(1.0f + __expf(2.0f * z)); hv[e] = 0.5f * t * (1.0f + th); } }
;                 const float* wp = cw2 + (size_t)kv * 256 * 64 + lane; float a = 0.f;
; #pragma unroll
;                 for (int k = 0; k < 256; ++k) { const float hk = __uint_as_float(__builtin_amdgcn_readlane(__float_as_uint(hv[k & 3]), k >> 2)); a = fmaf(hk, wp[k * 64], a); }
	v_mfma_f32_16x16x4_f32 v[64:67], v16, v152, v[64:67]
	v_mul_f32_e32 v224, v24, v24
	v_mul_f32_e32 v224, v224, v24
	v_fma_f32 v225, s16, v224, v24
	v_mfma_f32_16x16x4_f32 v[68:71], v16, v153, v[68:71]
	v_mul_f32_e32 v225, s18, v225
	v_exp_f32_e32 v226, v225
	v_mul_f32_e32 v227, 0.5, v24
	v_mfma_f32_16x16x4_f32 v[72:75], v16, v154, v[72:75]
	v_add_f32_e32 v226, 1.0, v226
	v_rcp_f32_e32 v226, v226
	v_mfma_f32_16x16x4_f32 v[76:79], v16, v155, v[76:79]
	v_fma_f32 v226, v226, -2.0, 1.0
	v_fma_f32 v24, v227, v226, v227
	v_mfma_f32_16x16x4_f32 v[64:67], v17, v156, v[64:67]
	v_mul_f32_e32 v224, v25, v25
	v_mul_f32_e32 v224, v224, v25
	v_fma_f32 v225, s16, v224, v25
	v_mfma_f32_16x16x4_f32 v[68:71], v17, v157, v[68:71]
	v_mul_f32_e32 v225, s18, v225
	v_exp_f32_e32 v226, v225
	v_mul_f32_e32 v227, 0.5, v25
	v_mfma_f32_16x16x4_f32 v[72:75], v17, v158, v[72:75]
	v_add_f32_e32 v226, 1.0, v226
	v_rcp_f32_e32 v226, v226
	v_mfma_f32_16x16x4_f32 v[76:79], v17, v159, v[76:79]
	v_fma_f32 v226, v226, -2.0, 1.0
	v_fma_f32 v25, v227, v226, v227
	v_mfma_f32_16x16x4_f32 v[64:67], v18, v160, v[64:67]
	v_mul_f32_e32 v224, v26, v26
	v_mul_f32_e32 v224, v224, v26
	v_fma_f32 v225, s16, v224, v26
	v_mfma_f32_16x16x4_f32 v[68:71], v18, v161, v[68:71]
	v_mul_f32_e32 v225, s18, v225
	v_exp_f32_e32 v226, v225
	v_mul_f32_e32 v227, 0.5, v26
	v_mfma_f32_16x16x4_f32 v[72:75], v18, v162, v[72:75]
	v_add_f32_e32 v226, 1.0, v226
	v_rcp_f32_e32 v226, v226
	v_mfma_f32_16x16x4_f32 v[76:79], v18, v163, v[76:79]
	v_fma_f32 v226, v226, -2.0, 1.0
	v_fma_f32 v26, v227, v226, v227
	v_mfma_f32_16x16x4_f32 v[64:67], v19, v170, v[64:67]
	v_mul_f32_e32 v224, v27, v27
	v_mul_f32_e32 v224, v224, v27
	v_fma_f32 v225, s16, v224, v27
	v_mfma_f32_16x16x4_f32 v[68:71], v19, v171, v[68:71]
	v_mul_f32_e32 v225, s18, v225
	v_exp_f32_e32 v226, v225
	v_mul_f32_e32 v227, 0.5, v27
	v_mfma_f32_16x16x4_f32 v[72:75], v19, v172, v[72:75]
	v_add_f32_e32 v226, 1.0, v226
	v_rcp_f32_e32 v226, v226
	v_mfma_f32_16x16x4_f32 v[76:79], v19, v173, v[76:79]
	v_fma_f32 v226, v226, -2.0, 1.0
	v_fma_f32 v27, v227, v226, v227
	v_mfma_f32_16x16x4_f32 v[64:67], v20, v174, v[64:67]
	v_mul_f32_e32 v224, v28, v28
	v_mul_f32_e32 v224, v224, v28
	v_fma_f32 v225, s16, v224, v28
	v_mfma_f32_16x16x4_f32 v[68:71], v20, v175, v[68:71]
	v_mul_f32_e32 v225, s18, v225
	v_exp_f32_e32 v226, v225
	v_mul_f32_e32 v227, 0.5, v28
	v_mfma_f32_16x16x4_f32 v[72:75], v20, v176, v[72:75]
	v_add_f32_e32 v226, 1.0, v226
	v_rcp_f32_e32 v226, v226
	v_mfma_f32_16x16x4_f32 v[76:79], v20, v177, v[76:79]
	v_fma_f32 v226, v226, -2.0, 1.0
	v_fma_f32 v28, v227, v226, v227
	v_mfma_f32_16x16x4_f32 v[64:67], v21, v178, v[64:67]
	v_mul_f32_e32 v224, v29, v29
	v_mul_f32_e32 v224, v224, v29
	v_fma_f32 v225, s16, v224, v29
	v_mfma_f32_16x16x4_f32 v[68:71], v21, v179, v[68:71]
	v_mul_f32_e32 v225, s18, v225
	v_exp_f32_e32 v226, v225
	v_mul_f32_e32 v227, 0.5, v29
	v_mfma_f32_16x16x4_f32 v[72:75], v21, v180, v[72:75]
	v_add_f32_e32 v226, 1.0, v226
	v_rcp_f32_e32 v226, v226
	v_mfma_f32_16x16x4_f32 v[76:79], v21, v181, v[76:79]
	v_fma_f32 v226, v226, -2.0, 1.0
	v_fma_f32 v29, v227, v226, v227
	v_mfma_f32_16x16x4_f32 v[64:67], v22, v182, v[64:67]
	v_mul_f32_e32 v224, v30, v30
	v_mul_f32_e32 v224, v224, v30
	v_fma_f32 v225, s16, v224, v30
	v_mfma_f32_16x16x4_f32 v[68:71], v22, v183, v[68:71]
	v_mul_f32_e32 v225, s18, v225
	v_exp_f32_e32 v226, v225
	v_mul_f32_e32 v227, 0.5, v30
	v_mfma_f32_16x16x4_f32 v[72:75], v22, v184, v[72:75]
	v_add_f32_e32 v226, 1.0, v226
	v_rcp_f32_e32 v226, v226
	v_mfma_f32_16x16x4_f32 v[76:79], v22, v185, v[76:79]
	v_fma_f32 v226, v226, -2.0, 1.0
	v_fma_f32 v30, v227, v226, v227
	v_mfma_f32_16x16x4_f32 v[64:67], v23, v220, v[64:67]
	v_mul_f32_e32 v224, v31, v31
	v_mul_f32_e32 v224, v224, v31
	v_fma_f32 v225, s16, v224, v31
	v_mfma_f32_16x16x4_f32 v[68:71], v23, v221, v[68:71]
	v_mul_f32_e32 v225, s18, v225
	v_exp_f32_e32 v226, v225
	v_mul_f32_e32 v227, 0.5, v31
	v_mfma_f32_16x16x4_f32 v[72:75], v23, v222, v[72:75]
	v_add_f32_e32 v226, 1.0, v226
	v_rcp_f32_e32 v226, v226
	v_mfma_f32_16x16x4_f32 v[76:79], v23, v223, v[76:79]
	v_fma_f32 v226, v226, -2.0, 1.0
	v_fma_f32 v31, v227, v226, v227
	global_load_dwordx4 v[152:155], v249, s[10:11]
	global_load_dwordx4 v[156:159], v249, s[10:11] offset:256
	global_load_dwordx4 v[160:163], v249, s[10:11] offset:512
	global_load_dwordx4 v[170:173], v249, s[10:11] offset:768
	global_load_dwordx4 v[174:177], v249, s[10:11] offset:1024
	global_load_dwordx4 v[178:181], v249, s[10:11] offset:1280
	global_load_dwordx4 v[182:185], v249, s[10:11] offset:1536
	global_load_dwordx4 v[220:223], v249, s[10:11] offset:1792
	s_add_u32 s10, s10, 0x800
	s_addc_u32 s11, s11, 0
	s_waitcnt vmcnt(16)
; __global__ void __launch_bounds__(512, 2) hybrid_fwd(Params P) {
;     ...
;                     for (int e = 0; e < 4; ++e) { const float t = hv[e], z = 0.7978845608028654f * (t + 0.044715f * t * t * t);
;                         const float th = 1.0f - 2.0f * __builtin_amdgcn_rcpf(1.0f + __expf(2.0f * z)); hv[e] = 0.5f * t * (1.0f + th); } }
;                 const float* wp = cw2 + (size_t)kv * 256 * 64 + lane; float a = 0.f;
; #pragma unroll
;                 for (int k = 0; k < 256; ++k) { const float hk = __uint_as_float(__builtin_amdgcn_readlane(__float_as_uint(hv[k & 3]), k >> 2)); a = fmaf(hk, wp[k * 64], a); }
	v_mfma_f32_16x16x4_f32 v[64:67], v24, v82, v[64:67]
	v_mul_f32_e32 v224, v32, v32
	v_mul_f32_e32 v224, v224, v32
	v_fma_f32 v225, s16, v224, v32
	v_mfma_f32_16x16x4_f32 v[68:71], v24, v83, v[68:71]
	v_mul_f32_e32 v225, s18, v225
	v_exp_f32_e32 v226, v225
	v_mul_f32_e32 v227, 0.5, v32
	v_mfma_f32_16x16x4_f32 v[72:75], v24, v84, v[72:75]
	v_add_f32_e32 v226, 1.0, v226
	v_rcp_f32_e32 v226, v226
	v_mfma_f32_16x16x4_f32 v[76:79], v24, v85, v[76:79]
	v_fma_f32 v226, v226, -2.0, 1.0
	v_fma_f32 v32, v227, v226, v227
	v_mfma_f32_16x16x4_f32 v[64:67], v25, v86, v[64:67]
	v_mul_f32_e32 v224, v33, v33
	v_mul_f32_e32 v224, v224, v33
	v_fma_f32 v225, s16, v224, v33
	v_mfma_f32_16x16x4_f32 v[68:71], v25, v87, v[68:71]
	v_mul_f32_e32 v225, s18, v225
	v_exp_f32_e32 v226, v225
	v_mul_f32_e32 v227, 0.5, v33
	v_mfma_f32_16x16x4_f32 v[72:75], v25, v88, v[72:75]
	v_add_f32_e32 v226, 1.0, v226
	v_rcp_f32_e32 v226, v226
	v_mfma_f32_16x16x4_f32 v[76:79], v25, v89, v[76:79]
	v_fma_f32 v226, v226, -2.0, 1.0
	v_fma_f32 v33, v227, v226, v227
	v_mfma_f32_16x16x4_f32 v[64:67], v26, v90, v[64:67]
	v_mul_f32_e32 v224, v34, v34
	v_mul_f32_e32 v224, v224, v34
	v_fma_f32 v225, s16, v224, v34
	v_mfma_f32_16x16x4_f32 v[68:71], v26, v91, v[68:71]
	v_mul_f32_e32 v225, s18, v225
	v_exp_f32_e32 v226, v225
	v_mul_f32_e32 v227, 0.5, v34
	v_mfma_f32_16x16x4_f32 v[72:75], v26, v92, v[72:75]
	v_add_f32_e32 v226, 1.0, v226
	v_rcp_f32_e32 v226, v226
	v_mfma_f32_16x16x4_f32 v[76:79], v26, v93, v[76:79]
	v_fma_f32 v226, v226, -2.0, 1.0
	v_fma_f32 v34, v227, v226, v227
	v_mfma_f32_16x16x4_f32 v[64:67], v27, v94, v[64:67]
	v_mul_f32_e32 v224, v35, v35
	v_mul_f32_e32 v224, v224, v35
	v_fma_f32 v225, s16, v224, v35
	v_mfma_f32_16x16x4_f32 v[68:71], v27, v95, v[68:71]
	v_mul_f32_e32 v225, s18, v225
	v_exp_f32_e32 v226, v225
	v_mul_f32_e32 v227, 0.5, v35
	v_mfma_f32_16x16x4_f32 v[72:75], v27, v96, v[72:75]
	v_add_f32_e32 v226, 1.0, v226
	v_rcp_f32_e32 v226, v226
	v_mfma_f32_16x16x4_f32 v[76:79], v27, v97, v[76:79]
	v_fma_f32 v226, v226, -2.0, 1.0
	v_fma_f32 v35, v227, v226, v227
	v_mfma_f32_16x16x4_f32 v[64:67], v28, v98, v[64:67]
	v_mul_f32_e32 v224, v36, v36
	v_mul_f32_e32 v224, v224, v36
	v_fma_f32 v225, s16, v224, v36
	v_mfma_f32_16x16x4_f32 v[68:71], v28, v99, v[68:71]
	v_mul_f32_e32 v225, s18, v225
	v_exp_f32_e32 v226, v225
	v_mul_f32_e32 v227, 0.5, v36
	v_mfma_f32_16x16x4_f32 v[72:75], v28, v100, v[72:75]
	v_add_f32_e32 v226, 1.0, v226
	v_rcp_f32_e32 v226, v226
	v_mfma_f32_16x16x4_f32 v[76:79], v28, v101, v[76:79]
	v_fma_f32 v226, v226, -2.0, 1.0
	v_fma_f32 v36, v227, v226, v227
	v_mfma_f32_16x16x4_f32 v[64:67], v29, v102, v[64:67]
	v_mul_f32_e32 v224, v37, v37
	v_mul_f32_e32 v224, v224, v37
	v_fma_f32 v225, s16, v224, v37
	v_mfma_f32_16x16x4_f32 v[68:71], v29, v103, v[68:71]
	v_mul_f32_e32 v225, s18, v225
	v_exp_f32_e32 v226, v225
	v_mul_f32_e32 v227, 0.5, v37
	v_mfma_f32_16x16x4_f32 v[72:75], v29, v104, v[72:75]
	v_add_f32_e32 v226, 1.0, v226
	v_rcp_f32_e32 v226, v226
	v_mfma_f32_16x16x4_f32 v[76:79], v29, v105, v[76:79]
	v_fma_f32 v226, v226, -2.0, 1.0
	v_fma_f32 v37, v227, v226, v227
	v_mfma_f32_16x16x4_f32 v[64:67], v30, v106, v[64:67]
	v_mul_f32_e32 v224, v38, v38
	v_mul_f32_e32 v224, v224, v38
	v_fma_f32 v225, s16, v224, v38
	v_mfma_f32_16x16x4_f32 v[68:71], v30, v107, v[68:71]
	v_mul_f32_e32 v225, s18, v225
	v_exp_f32_e32 v226, v225
	v_mul_f32_e32 v227, 0.5, v38
	v_mfma_f32_16x16x4_f32 v[72:75], v30, v108, v[72:75]
	v_add_f32_e32 v226, 1.0, v226
	v_rcp_f32_e32 v226, v226
	v_mfma_f32_16x16x4_f32 v[76:79], v30, v109, v[76:79]
	v_fma_f32 v226, v226, -2.0, 1.0
	v_fma_f32 v38, v227, v226, v227
	v_mfma_f32_16x16x4_f32 v[64:67], v31, v110, v[64:67]
	v_mul_f32_e32 v224, v39, v39
	v_mul_f32_e32 v224, v224, v39
	v_fma_f32 v225, s16, v224, v39
	v_mfma_f32_16x16x4_f32 v[68:71], v31, v111, v[68:71]
	v_mul_f32_e32 v225, s18, v225
	v_exp_f32_e32 v226, v225
	v_mul_f32_e32 v227, 0.5, v39
	v_mfma_f32_16x16x4_f32 v[72:75], v31, v112, v[72:75]
	v_add_f32_e32 v226, 1.0, v226
	v_rcp_f32_e32 v226, v226
	v_mfma_f32_16x16x4_f32 v[76:79], v31, v113, v[76:79]
	v_fma_f32 v226, v226, -2.0, 1.0
	v_fma_f32 v39, v227, v226, v227
	global_load_dwordx4 v[82:85], v249, s[10:11]
	global_load_dwordx4 v[86:89], v249, s[10:11] offset:256
	global_load_dwordx4 v[90:93], v249, s[10:11] offset:512
	global_load_dwordx4 v[94:97], v249, s[10:11] offset:768
	global_load_dwordx4 v[98:101], v249, s[10:11] offset:1024
	global_load_dwordx4 v[102:105], v249, s[10:11] offset:1280
	global_load_dwordx4 v[106:109], v249, s[10:11] offset:1536
	global_load_dwordx4 v[110:113], v249, s[10:11] offset:1792
	s_add_u32 s10, s10, 0x800
	s_addc_u32 s11, s11, 0
	s_waitcnt vmcnt(16)
; __global__ void __launch_bounds__(512, 2) hybrid_fwd(Params P) {
;     ...
;                     for (int e = 0; e < 4; ++e) { const float t = hv[e], z = 0.7978845608028654f * (t + 0.044715f * t * t * t);
;                         const float th = 1.0f - 2.0f * __builtin_amdgcn_rcpf(1.0f + __expf(2.0f * z)); hv[e] = 0.5f * t * (1.0f + th); } }
;                 const float* wp = cw2 + (size_t)kv * 256 * 64 + lane; float a = 0.f;
; #pragma unroll
;                 for (int k = 0; k < 256; ++k) { const float hk = __uint_as_float(__builtin_amdgcn_readlane(__float_as_uint(hv[k & 3]), k >> 2)); a = fmaf(hk, wp[k * 64], a); }
	v_mfma_f32_16x16x4_f32 v[64:67], v32, v114, v[64:67]
	v_mul_f32_e32 v224, v40, v40
	v_mul_f32_e32 v224, v224, v40
	v_fma_f32 v225, s16, v224, v40
	v_mfma_f32_16x16x4_f32 v[68:71], v32, v115, v[68:71]
	v_mul_f32_e32 v225, s18, v225
	v_exp_f32_e32 v226, v225
	v_mul_f32_e32 v227, 0.5, v40
	v_mfma_f32_16x16x4_f32 v[72:75], v32, v116, v[72:75]
	v_add_f32_e32 v226, 1.0, v226
	v_rcp_f32_e32 v226, v226
	v_mfma_f32_16x16x4_f32 v[76:79], v32, v117, v[76:79]
	v_fma_f32 v226, v226, -2.0, 1.0
	v_fma_f32 v40, v227, v226, v227
	v_mfma_f32_16x16x4_f32 v[64:67], v33, v118, v[64:67]
	v_mul_f32_e32 v224, v41, v41
	v_mul_f32_e32 v224, v224, v41
	v_fma_f32 v225, s16, v224, v41
	v_mfma_f32_16x16x4_f32 v[68:71], v33, v119, v[68:71]
	v_mul_f32_e32 v225, s18, v225
	v_exp_f32_e32 v226, v225
	v_mul_f32_e32 v227, 0.5, v41
	v_mfma_f32_16x16x4_f32 v[72:75], v33, v120, v[72:75]
	v_add_f32_e32 v226, 1.0, v226
	v_rcp_f32_e32 v226, v226
	v_mfma_f32_16x16x4_f32 v[76:79], v33, v121, v[76:79]
	v_fma_f32 v226, v226, -2.0, 1.0
	v_fma_f32 v41, v227, v226, v227
	v_mfma_f32_16x16x4_f32 v[64:67], v34, v122, v[64:67]
	v_mul_f32_e32 v224, v42, v42
	v_mul_f32_e32 v224, v224, v42
	v_fma_f32 v225, s16, v224, v42
	v_mfma_f32_16x16x4_f32 v[68:71], v34, v123, v[68:71]
	v_mul_f32_e32 v225, s18, v225
	v_exp_f32_e32 v226, v225
	v_mul_f32_e32 v227, 0.5, v42
	v_mfma_f32_16x16x4_f32 v[72:75], v34, v124, v[72:75]
	v_add_f32_e32 v226, 1.0, v226
	v_rcp_f32_e32 v226, v226
	v_mfma_f32_16x16x4_f32 v[76:79], v34, v125, v[76:79]
	v_fma_f32 v226, v226, -2.0, 1.0
	v_fma_f32 v42, v227, v226, v227
	v_mfma_f32_16x16x4_f32 v[64:67], v35, v126, v[64:67]
	v_mul_f32_e32 v224, v43, v43
	v_mul_f32_e32 v224, v224, v43
	v_fma_f32 v225, s16, v224, v43
	v_mfma_f32_16x16x4_f32 v[68:71], v35, v127, v[68:71]
	v_mul_f32_e32 v225, s18, v225
	v_exp_f32_e32 v226, v225
	v_mul_f32_e32 v227, 0.5, v43
	v_mfma_f32_16x16x4_f32 v[72:75], v35, v128, v[72:75]
	v_add_f32_e32 v226, 1.0, v226
	v_rcp_f32_e32 v226, v226
	v_mfma_f32_16x16x4_f32 v[76:79], v35, v129, v[76:79]
	v_fma_f32 v226, v226, -2.0, 1.0
	v_fma_f32 v43, v227, v226, v227
	v_mfma_f32_16x16x4_f32 v[64:67], v36, v130, v[64:67]
	v_mul_f32_e32 v224, v44, v44
	v_mul_f32_e32 v224, v224, v44
	v_fma_f32 v225, s16, v224, v44
	v_mfma_f32_16x16x4_f32 v[68:71], v36, v131, v[68:71]
	v_mul_f32_e32 v225, s18, v225
	v_exp_f32_e32 v226, v225
	v_mul_f32_e32 v227, 0.5, v44
	v_mfma_f32_16x16x4_f32 v[72:75], v36, v132, v[72:75]
	v_add_f32_e32 v226, 1.0, v226
	v_rcp_f32_e32 v226, v226
	v_mfma_f32_16x16x4_f32 v[76:79], v36, v133, v[76:79]
	v_fma_f32 v226, v226, -2.0, 1.0
	v_fma_f32 v44, v227, v226, v227
	v_mfma_f32_16x16x4_f32 v[64:67], v37, v134, v[64:67]
	v_mul_f32_e32 v224, v45, v45
	v_mul_f32_e32 v224, v224, v45
	v_fma_f32 v225, s16, v224, v45
	v_mfma_f32_16x16x4_f32 v[68:71], v37, v135, v[68:71]
	v_mul_f32_e32 v225, s18, v225
	v_exp_f32_e32 v226, v225
	v_mul_f32_e32 v227, 0.5, v45
	v_mfma_f32_16x16x4_f32 v[72:75], v37, v136, v[72:75]
	v_add_f32_e32 v226, 1.0, v226
	v_rcp_f32_e32 v226, v226
	v_mfma_f32_16x16x4_f32 v[76:79], v37, v137, v[76:79]
	v_fma_f32 v226, v226, -2.0, 1.0
	v_fma_f32 v45, v227, v226, v227
	v_mfma_f32_16x16x4_f32 v[64:67], v38, v138, v[64:67]
	v_mul_f32_e32 v224, v46, v46
	v_mul_f32_e32 v224, v224, v46
	v_fma_f32 v225, s16, v224, v46
	v_mfma_f32_16x16x4_f32 v[68:71], v38, v139, v[68:71]
	v_mul_f32_e32 v225, s18, v225
	v_exp_f32_e32 v226, v225
	v_mul_f32_e32 v227, 0.5, v46
	v_mfma_f32_16x16x4_f32 v[72:75], v38, v140, v[72:75]
	v_add_f32_e32 v226, 1.0, v226
	v_rcp_f32_e32 v226, v226
	v_mfma_f32_16x16x4_f32 v[76:79], v38, v141, v[76:79]
	v_fma_f32 v226, v226, -2.0, 1.0
	v_fma_f32 v46, v227, v226, v227
	v_mfma_f32_16x16x4_f32 v[64:67], v39, v142, v[64:67]
	v_mul_f32_e32 v224, v47, v47
	v_mul_f32_e32 v224, v224, v47
	v_fma_f32 v225, s16, v224, v47
	v_mfma_f32_16x16x4_f32 v[68:71], v39, v143, v[68:71]
	v_mul_f32_e32 v225, s18, v225
	v_exp_f32_e32 v226, v225
	v_mul_f32_e32 v227, 0.5, v47
	v_mfma_f32_16x16x4_f32 v[72:75], v39, v144, v[72:75]
	v_add_f32_e32 v226, 1.0, v226
	v_rcp_f32_e32 v226, v226
	v_mfma_f32_16x16x4_f32 v[76:79], v39, v145, v[76:79]
	v_fma_f32 v226, v226, -2.0, 1.0
	v_fma_f32 v47, v227, v226, v227
	global_load_dwordx4 v[114:117], v249, s[10:11]
	global_load_dwordx4 v[118:121], v249, s[10:11] offset:256
	global_load_dwordx4 v[122:125], v249, s[10:11] offset:512
	global_load_dwordx4 v[126:129], v249, s[10:11] offset:768
	global_load_dwordx4 v[130:133], v249, s[10:11] offset:1024
	global_load_dwordx4 v[134:137], v249, s[10:11] offset:1280
	global_load_dwordx4 v[138:141], v249, s[10:11] offset:1536
	global_load_dwordx4 v[142:145], v249, s[10:11] offset:1792
	s_add_u32 s10, s10, 0x800
	s_addc_u32 s11, s11, 0
	s_waitcnt vmcnt(16)
; __global__ void __launch_bounds__(512, 2) hybrid_fwd(Params P) {
;     ...
;                     for (int e = 0; e < 4; ++e) { const float t = hv[e], z = 0.7978845608028654f * (t + 0.044715f * t * t * t);
;                         const float th = 1.0f - 2.0f * __builtin_amdgcn_rcpf(1.0f + __expf(2.0f * z)); hv[e] = 0.5f * t * (1.0f + th); } }
;                 const float* wp = cw2 + (size_t)kv * 256 * 64 + lane; float a = 0.f;
; #pragma unroll
;                 for (int k = 0; k < 256; ++k) { const float hk = __uint_as_float(__builtin_amdgcn_readlane(__float_as_uint(hv[k & 3]), k >> 2)); a = fmaf(hk, wp[k * 64], a); }
	v_mfma_f32_16x16x4_f32 v[64:67], v40, v152, v[64:67]
	v_mul_f32_e32 v224, v48, v48
	v_mul_f32_e32 v224, v224, v48
	v_fma_f32 v225, s16, v224, v48
	v_mfma_f32_16x16x4_f32 v[68:71], v40, v153, v[68:71]
	v_mul_f32_e32 v225, s18, v225
	v_exp_f32_e32 v226, v225
	v_mul_f32_e32 v227, 0.5, v48
	v_mfma_f32_16x16x4_f32 v[72:75], v40, v154, v[72:75]
	v_add_f32_e32 v226, 1.0, v226
	v_rcp_f32_e32 v226, v226
	v_mfma_f32_16x16x4_f32 v[76:79], v40, v155, v[76:79]
	v_fma_f32 v226, v226, -2.0, 1.0
	v_fma_f32 v48, v227, v226, v227
	v_mfma_f32_16x16x4_f32 v[64:67], v41, v156, v[64:67]
	v_mul_f32_e32 v224, v49, v49
	v_mul_f32_e32 v224, v224, v49
	v_fma_f32 v225, s16, v224, v49
	v_mfma_f32_16x16x4_f32 v[68:71], v41, v157, v[68:71]
	v_mul_f32_e32 v225, s18, v225
	v_exp_f32_e32 v226, v225
	v_mul_f32_e32 v227, 0.5, v49
	v_mfma_f32_16x16x4_f32 v[72:75], v41, v158, v[72:75]
	v_add_f32_e32 v226, 1.0, v226
	v_rcp_f32_e32 v226, v226
	v_mfma_f32_16x16x4_f32 v[76:79], v41, v159, v[76:79]
	v_fma_f32 v226, v226, -2.0, 1.0
	v_fma_f32 v49, v227, v226, v227
	v_mfma_f32_16x16x4_f32 v[64:67], v42, v160, v[64:67]
	v_mul_f32_e32 v224, v50, v50
	v_mul_f32_e32 v224, v224, v50
	v_fma_f32 v225, s16, v224, v50
	v_mfma_f32_16x16x4_f32 v[68:71], v42, v161, v[68:71]
	v_mul_f32_e32 v225, s18, v225
	v_exp_f32_e32 v226, v225
	v_mul_f32_e32 v227, 0.5, v50
	v_mfma_f32_16x16x4_f32 v[72:75], v42, v162, v[72:75]
	v_add_f32_e32 v226, 1.0, v226
	v_rcp_f32_e32 v226, v226
	v_mfma_f32_16x16x4_f32 v[76:79], v42, v163, v[76:79]
	v_fma_f32 v226, v226, -2.0, 1.0
	v_fma_f32 v50, v227, v226, v227
	v_mfma_f32_16x16x4_f32 v[64:67], v43, v170, v[64:67]
	v_mul_f32_e32 v224, v51, v51
	v_mul_f32_e32 v224, v224, v51
	v_fma_f32 v225, s16, v224, v51
	v_mfma_f32_16x16x4_f32 v[68:71], v43, v171, v[68:71]
	v_mul_f32_e32 v225, s18, v225
	v_exp_f32_e32 v226, v225
	v_mul_f32_e32 v227, 0.5, v51
	v_mfma_f32_16x16x4_f32 v[72:75], v43, v172, v[72:75]
	v_add_f32_e32 v226, 1.0, v226
	v_rcp_f32_e32 v226, v226
	v_mfma_f32_16x16x4_f32 v[76:79], v43, v173, v[76:79]
	v_fma_f32 v226, v226, -2.0, 1.0
	v_fma_f32 v51, v227, v226, v227
	v_mfma_f32_16x16x4_f32 v[64:67], v44, v174, v[64:67]
	v_mul_f32_e32 v224, v52, v52
	v_mul_f32_e32 v224, v224, v52
	v_fma_f32 v225, s16, v224, v52
	v_mfma_f32_16x16x4_f32 v[68:71], v44, v175, v[68:71]
	v_mul_f32_e32 v225, s18, v225
	v_exp_f32_e32 v226, v225
	v_mul_f32_e32 v227, 0.5, v52
	v_mfma_f32_16x16x4_f32 v[72:75], v44, v176, v[72:75]
	v_add_f32_e32 v226, 1.0, v226
	v_rcp_f32_e32 v226, v226
	v_mfma_f32_16x16x4_f32 v[76:79], v44, v177, v[76:79]
	v_fma_f32 v226, v226, -2.0, 1.0
	v_fma_f32 v52, v227, v226, v227
	v_mfma_f32_16x16x4_f32 v[64:67], v45, v178, v[64:67]
	v_mul_f32_e32 v224, v53, v53
	v_mul_f32_e32 v224, v224, v53
	v_fma_f32 v225, s16, v224, v53
	v_mfma_f32_16x16x4_f32 v[68:71], v45, v179, v[68:71]
	v_mul_f32_e32 v225, s18, v225
	v_exp_f32_e32 v226, v225
	v_mul_f32_e32 v227, 0.5, v53
	v_mfma_f32_16x16x4_f32 v[72:75], v45, v180, v[72:75]
	v_add_f32_e32 v226, 1.0, v226
	v_rcp_f32_e32 v226, v226
	v_mfma_f32_16x16x4_f32 v[76:79], v45, v181, v[76:79]
	v_fma_f32 v226, v226, -2.0, 1.0
	v_fma_f32 v53, v227, v226, v227
	v_mfma_f32_16x16x4_f32 v[64:67], v46, v182, v[64:67]
	v_mul_f32_e32 v224, v54, v54
	v_mul_f32_e32 v224, v224, v54
	v_fma_f32 v225, s16, v224, v54
	v_mfma_f32_16x16x4_f32 v[68:71], v46, v183, v[68:71]
	v_mul_f32_e32 v225, s18, v225
	v_exp_f32_e32 v226, v225
	v_mul_f32_e32 v227, 0.5, v54
	v_mfma_f32_16x16x4_f32 v[72:75], v46, v184, v[72:75]
	v_add_f32_e32 v226, 1.0, v226
	v_rcp_f32_e32 v226, v226
	v_mfma_f32_16x16x4_f32 v[76:79], v46, v185, v[76:79]
	v_fma_f32 v226, v226, -2.0, 1.0
	v_fma_f32 v54, v227, v226, v227
	v_mfma_f32_16x16x4_f32 v[64:67], v47, v220, v[64:67]
	v_mul_f32_e32 v224, v55, v55
	v_mul_f32_e32 v224, v224, v55
	v_fma_f32 v225, s16, v224, v55
	v_mfma_f32_16x16x4_f32 v[68:71], v47, v221, v[68:71]
	v_mul_f32_e32 v225, s18, v225
	v_exp_f32_e32 v226, v225
	v_mul_f32_e32 v227, 0.5, v55
	v_mfma_f32_16x16x4_f32 v[72:75], v47, v222, v[72:75]
	v_add_f32_e32 v226, 1.0, v226
	v_rcp_f32_e32 v226, v226
	v_mfma_f32_16x16x4_f32 v[76:79], v47, v223, v[76:79]
	v_fma_f32 v226, v226, -2.0, 1.0
	v_fma_f32 v55, v227, v226, v227
	s_waitcnt vmcnt(8)
	v_mfma_f32_16x16x4_f32 v[64:67], v48, v82, v[64:67]
	v_mul_f32_e32 v224, v56, v56
	v_mul_f32_e32 v224, v224, v56
	v_fma_f32 v225, s16, v224, v56
	v_mfma_f32_16x16x4_f32 v[68:71], v48, v83, v[68:71]
	v_mul_f32_e32 v225, s18, v225
	v_exp_f32_e32 v226, v225
	v_mul_f32_e32 v227, 0.5, v56
	v_mfma_f32_16x16x4_f32 v[72:75], v48, v84, v[72:75]
	v_add_f32_e32 v226, 1.0, v226
	v_rcp_f32_e32 v226, v226
	v_mfma_f32_16x16x4_f32 v[76:79], v48, v85, v[76:79]
	v_fma_f32 v226, v226, -2.0, 1.0
	v_fma_f32 v56, v227, v226, v227
	v_mfma_f32_16x16x4_f32 v[64:67], v49, v86, v[64:67]
	v_mul_f32_e32 v224, v57, v57
	v_mul_f32_e32 v224, v224, v57
	v_fma_f32 v225, s16, v224, v57
	v_mfma_f32_16x16x4_f32 v[68:71], v49, v87, v[68:71]
	v_mul_f32_e32 v225, s18, v225
	v_exp_f32_e32 v226, v225
	v_mul_f32_e32 v227, 0.5, v57
	v_mfma_f32_16x16x4_f32 v[72:75], v49, v88, v[72:75]
	v_add_f32_e32 v226, 1.0, v226
	v_rcp_f32_e32 v226, v226
	v_mfma_f32_16x16x4_f32 v[76:79], v49, v89, v[76:79]
	v_fma_f32 v226, v226, -2.0, 1.0
	v_fma_f32 v57, v227, v226, v227
	v_mfma_f32_16x16x4_f32 v[64:67], v50, v90, v[64:67]
	v_mul_f32_e32 v224, v58, v58
	v_mul_f32_e32 v224, v224, v58
	v_fma_f32 v225, s16, v224, v58
	v_mfma_f32_16x16x4_f32 v[68:71], v50, v91, v[68:71]
	v_mul_f32_e32 v225, s18, v225
	v_exp_f32_e32 v226, v225
	v_mul_f32_e32 v227, 0.5, v58
	v_mfma_f32_16x16x4_f32 v[72:75], v50, v92, v[72:75]
	v_add_f32_e32 v226, 1.0, v226
	v_rcp_f32_e32 v226, v226
	v_mfma_f32_16x16x4_f32 v[76:79], v50, v93, v[76:79]
; __global__ void __launch_bounds__(512, 2) hybrid_fwd(Params P) {
;     ...
;                     for (int e = 0; e < 4; ++e) { const float t = hv[e], z = 0.7978845608028654f * (t + 0.044715f * t * t * t);
;                         const float th = 1.0f - 2.0f * __builtin_amdgcn_rcpf(1.0f + __expf(2.0f * z)); hv[e] = 0.5f * t * (1.0f + th); } }
;                 const float* wp = cw2 + (size_t)kv * 256 * 64 + lane; float a = 0.f;
; #pragma unroll
;                 for (int k = 0; k < 256; ++k) { const float hk = __uint_as_float(__builtin_amdgcn_readlane(__float_as_uint(hv[k & 3]), k >> 2)); a = fmaf(hk, wp[k * 64], a); }
	v_fma_f32 v226, v226, -2.0, 1.0
	v_fma_f32 v58, v227, v226, v227
	v_mfma_f32_16x16x4_f32 v[64:67], v51, v94, v[64:67]
	v_mul_f32_e32 v224, v59, v59
	v_mul_f32_e32 v224, v224, v59
	v_fma_f32 v225, s16, v224, v59
	v_mfma_f32_16x16x4_f32 v[68:71], v51, v95, v[68:71]
	v_mul_f32_e32 v225, s18, v225
	v_exp_f32_e32 v226, v225
	v_mul_f32_e32 v227, 0.5, v59
	v_mfma_f32_16x16x4_f32 v[72:75], v51, v96, v[72:75]
	v_add_f32_e32 v226, 1.0, v226
	v_rcp_f32_e32 v226, v226
	v_mfma_f32_16x16x4_f32 v[76:79], v51, v97, v[76:79]
	v_fma_f32 v226, v226, -2.0, 1.0
	v_fma_f32 v59, v227, v226, v227
	v_mfma_f32_16x16x4_f32 v[64:67], v52, v98, v[64:67]
	v_mul_f32_e32 v224, v60, v60
	v_mul_f32_e32 v224, v224, v60
	v_fma_f32 v225, s16, v224, v60
	v_mfma_f32_16x16x4_f32 v[68:71], v52, v99, v[68:71]
	v_mul_f32_e32 v225, s18, v225
	v_exp_f32_e32 v226, v225
	v_mul_f32_e32 v227, 0.5, v60
	v_mfma_f32_16x16x4_f32 v[72:75], v52, v100, v[72:75]
	v_add_f32_e32 v226, 1.0, v226
	v_rcp_f32_e32 v226, v226
	v_mfma_f32_16x16x4_f32 v[76:79], v52, v101, v[76:79]
	v_fma_f32 v226, v226, -2.0, 1.0
	v_fma_f32 v60, v227, v226, v227
	v_mfma_f32_16x16x4_f32 v[64:67], v53, v102, v[64:67]
	v_mul_f32_e32 v224, v61, v61
	v_mul_f32_e32 v224, v224, v61
	v_fma_f32 v225, s16, v224, v61
	v_mfma_f32_16x16x4_f32 v[68:71], v53, v103, v[68:71]
	v_mul_f32_e32 v225, s18, v225
	v_exp_f32_e32 v226, v225
	v_mul_f32_e32 v227, 0.5, v61
	v_mfma_f32_16x16x4_f32 v[72:75], v53, v104, v[72:75]
	v_add_f32_e32 v226, 1.0, v226
	v_rcp_f32_e32 v226, v226
	v_mfma_f32_16x16x4_f32 v[76:79], v53, v105, v[76:79]
	v_fma_f32 v226, v226, -2.0, 1.0
	v_fma_f32 v61, v227, v226, v227
	v_mfma_f32_16x16x4_f32 v[64:67], v54, v106, v[64:67]
	v_mul_f32_e32 v224, v62, v62
	v_mul_f32_e32 v224, v224, v62
	v_fma_f32 v225, s16, v224, v62
	v_mfma_f32_16x16x4_f32 v[68:71], v54, v107, v[68:71]
	v_mul_f32_e32 v225, s18, v225
	v_exp_f32_e32 v226, v225
	v_mul_f32_e32 v227, 0.5, v62
	v_mfma_f32_16x16x4_f32 v[72:75], v54, v108, v[72:75]
	v_add_f32_e32 v226, 1.0, v226
	v_rcp_f32_e32 v226, v226
	v_mfma_f32_16x16x4_f32 v[76:79], v54, v109, v[76:79]
	v_fma_f32 v226, v226, -2.0, 1.0
	v_fma_f32 v62, v227, v226, v227
	v_mfma_f32_16x16x4_f32 v[64:67], v55, v110, v[64:67]
	v_mul_f32_e32 v224, v63, v63
	v_mul_f32_e32 v224, v224, v63
	v_fma_f32 v225, s16, v224, v63
	v_mfma_f32_16x16x4_f32 v[68:71], v55, v111, v[68:71]
	v_mul_f32_e32 v225, s18, v225
	v_exp_f32_e32 v226, v225
	v_mul_f32_e32 v227, 0.5, v63
	v_mfma_f32_16x16x4_f32 v[72:75], v55, v112, v[72:75]
	v_add_f32_e32 v226, 1.0, v226
	v_rcp_f32_e32 v226, v226
	v_mfma_f32_16x16x4_f32 v[76:79], v55, v113, v[76:79]
	v_fma_f32 v226, v226, -2.0, 1.0
	v_fma_f32 v63, v227, v226, v227
	s_waitcnt vmcnt(0)
	v_mfma_f32_16x16x4_f32 v[64:67], v56, v114, v[64:67]
	v_mfma_f32_16x16x4_f32 v[68:71], v56, v115, v[68:71]
	v_mfma_f32_16x16x4_f32 v[72:75], v56, v116, v[72:75]
	v_mfma_f32_16x16x4_f32 v[76:79], v56, v117, v[76:79]
	v_mfma_f32_16x16x4_f32 v[64:67], v57, v118, v[64:67]
	v_mfma_f32_16x16x4_f32 v[68:71], v57, v119, v[68:71]
	v_mfma_f32_16x16x4_f32 v[72:75], v57, v120, v[72:75]
	v_mfma_f32_16x16x4_f32 v[76:79], v57, v121, v[76:79]
	v_mfma_f32_16x16x4_f32 v[64:67], v58, v122, v[64:67]
	v_mfma_f32_16x16x4_f32 v[68:71], v58, v123, v[68:71]
	v_mfma_f32_16x16x4_f32 v[72:75], v58, v124, v[72:75]
	v_mfma_f32_16x16x4_f32 v[76:79], v58, v125, v[76:79]
	v_mfma_f32_16x16x4_f32 v[64:67], v59, v126, v[64:67]
	v_mfma_f32_16x16x4_f32 v[68:71], v59, v127, v[68:71]
	v_mfma_f32_16x16x4_f32 v[72:75], v59, v128, v[72:75]
	v_mfma_f32_16x16x4_f32 v[76:79], v59, v129, v[76:79]
	v_mfma_f32_16x16x4_f32 v[64:67], v60, v130, v[64:67]
	v_mfma_f32_16x16x4_f32 v[68:71], v60, v131, v[68:71]
	v_mfma_f32_16x16x4_f32 v[72:75], v60, v132, v[72:75]
	v_mfma_f32_16x16x4_f32 v[76:79], v60, v133, v[76:79]
	v_mfma_f32_16x16x4_f32 v[64:67], v61, v134, v[64:67]
	v_mfma_f32_16x16x4_f32 v[68:71], v61, v135, v[68:71]
	v_mfma_f32_16x16x4_f32 v[72:75], v61, v136, v[72:75]
	v_mfma_f32_16x16x4_f32 v[76:79], v61, v137, v[76:79]
	v_mfma_f32_16x16x4_f32 v[64:67], v62, v138, v[64:67]
	v_mfma_f32_16x16x4_f32 v[68:71], v62, v139, v[68:71]
	v_mfma_f32_16x16x4_f32 v[72:75], v62, v140, v[72:75]
	v_mfma_f32_16x16x4_f32 v[76:79], v62, v141, v[76:79]
	v_mfma_f32_16x16x4_f32 v[64:67], v63, v142, v[64:67]
	v_mfma_f32_16x16x4_f32 v[68:71], v63, v143, v[68:71]
	v_mfma_f32_16x16x4_f32 v[72:75], v63, v144, v[72:75]
	v_mfma_f32_16x16x4_f32 v[76:79], v63, v145, v[76:79]
	s_nop 7
	s_nop 7
	v_lshl_add_u32 v253, v246, 2, s8
	v_and_b32_e32 v253, 0x1ff, v253
	v_cmp_eq_u32_e32 vcc, 0x1fc, v253
	s_mov_b64 s[18:19], vcc
	s_cmp_lg_u32 s9, 0
	s_cbranch_scc1 .Lphd_v
; __device__ __forceinline__ unsigned pk2(float lo, float hi) { f32x2_t v = {lo, hi}; bf16x2_t b = __builtin_convertvector(v, bf16x2_t); return __builtin_bit_cast(unsigned, b); }
; __device__ __forceinline__ float wave_sum(float v) { v += __shfl_xor(v, 1); v += __shfl_xor(v, 2); v += __shfl_xor(v, 4); v += __shfl_xor(v, 8); v += __shfl_xor(v, 16); v += __shfl_xor(v, 32); return v; }
; __global__ void __launch_bounds__(512, 2) hybrid_fwd(Params P) {
;     ...
;                 if (kv == 0) { const float ss = wave_sum(a * a); float y = a * __builtin_amdgcn_rsqf(ss * (1.0f / 64.0f) + 1e-6f) * nkn[lane]; if (n == 511) y = 0.f;
;                     KC[((size_t)bg * 512 + n) * 64 + lane] = (bf16_t)(pk2(y, 0.f) & 0xffffu); }
	v_mul_f32_e32 v0, v64, v64
	v_mul_f32_e32 v1, v65, v65
	v_mul_f32_e32 v2, v66, v66
	v_mul_f32_e32 v3, v67, v67
	v_fmac_f32_e32 v0, v68, v68
	v_fmac_f32_e32 v1, v69, v69
	v_fmac_f32_e32 v2, v70, v70
	v_fmac_f32_e32 v3, v71, v71
	v_fmac_f32_e32 v0, v72, v72
	v_fmac_f32_e32 v1, v73, v73
	v_fmac_f32_e32 v2, v74, v74
	v_fmac_f32_e32 v3, v75, v75
	v_fmac_f32_e32 v0, v76, v76
	v_fmac_f32_e32 v1, v77, v77
	v_fmac_f32_e32 v2, v78, v78
	v_fmac_f32_e32 v3, v79, v79
	s_nop 1
	v_add_f32_dpp v4, v0, v0 row_ror:8 row_mask:0xf bank_mask:0xf
	v_add_f32_dpp v5, v1, v1 row_ror:8 row_mask:0xf bank_mask:0xf
	v_add_f32_dpp v6, v2, v2 row_ror:8 row_mask:0xf bank_mask:0xf
	v_add_f32_dpp v7, v3, v3 row_ror:8 row_mask:0xf bank_mask:0xf
	s_nop 1
	v_mov_b32_e32 v0, v4
	v_mov_b32_e32 v1, v5
	v_mov_b32_e32 v2, v6
	v_mov_b32_e32 v3, v7
	s_nop 1
	v_add_f32_dpp v4, v0, v0 row_ror:4 row_mask:0xf bank_mask:0xf
	v_add_f32_dpp v5, v1, v1 row_ror:4 row_mask:0xf bank_mask:0xf
	v_add_f32_dpp v6, v2, v2 row_ror:4 row_mask:0xf bank_mask:0xf
	v_add_f32_dpp v7, v3, v3 row_ror:4 row_mask:0xf bank_mask:0xf
	s_nop 1
	v_mov_b32_e32 v0, v4
	v_mov_b32_e32 v1, v5
	v_mov_b32_e32 v2, v6
	v_mov_b32_e32 v3, v7
	s_nop 1
	v_add_f32_dpp v4, v0, v0 row_ror:2 row_mask:0xf bank_mask:0xf
	v_add_f32_dpp v5, v1, v1 row_ror:2 row_mask:0xf bank_mask:0xf
	v_add_f32_dpp v6, v2, v2 row_ror:2 row_mask:0xf bank_mask:0xf
	v_add_f32_dpp v7, v3, v3 row_ror:2 row_mask:0xf bank_mask:0xf
	s_nop 1
	v_mov_b32_e32 v0, v4
	v_mov_b32_e32 v1, v5
	v_mov_b32_e32 v2, v6
	v_mov_b32_e32 v3, v7
	s_nop 1
	v_add_f32_dpp v4, v0, v0 row_ror:1 row_mask:0xf bank_mask:0xf
	v_add_f32_dpp v5, v1, v1 row_ror:1 row_mask:0xf bank_mask:0xf
	v_add_f32_dpp v6, v2, v2 row_ror:1 row_mask:0xf bank_mask:0xf
	v_add_f32_dpp v7, v3, v3 row_ror:1 row_mask:0xf bank_mask:0xf
	s_nop 1
	v_mov_b32_e32 v0, v4
	v_mov_b32_e32 v1, v5
	v_mov_b32_e32 v2, v6
	v_mov_b32_e32 v3, v7
	v_fmamk_f32 v0, v0, 0x3c800000, v147
	v_fmamk_f32 v1, v1, 0x3c800000, v147
	v_fmamk_f32 v2, v2, 0x3c800000, v147
	v_fmamk_f32 v3, v3, 0x3c800000, v147
	v_rsq_f32_e32 v0, v0
	v_rsq_f32_e32 v1, v1
	v_rsq_f32_e32 v2, v2
	v_rsq_f32_e32 v3, v3
	s_nop 0
	v_mul_f32_e32 v64, v64, v0
	v_mul_f32_e32 v65, v65, v1
	v_mul_f32_e32 v66, v66, v2
	v_mul_f32_e32 v67, v67, v3
	v_mul_f32_e32 v68, v68, v0
	v_mul_f32_e32 v69, v69, v1
	v_mul_f32_e32 v70, v70, v2
	v_mul_f32_e32 v71, v71, v3
	v_mul_f32_e32 v72, v72, v0
	v_mul_f32_e32 v73, v73, v1
	v_mul_f32_e32 v74, v74, v2
	v_mul_f32_e32 v75, v75, v3
	v_mul_f32_e32 v76, v76, v0
	v_mul_f32_e32 v77, v77, v1
	v_mul_f32_e32 v78, v78, v2
	v_mul_f32_e32 v79, v79, v3
	v_mul_f32_e32 v64, v64, v240
	v_mul_f32_e32 v65, v65, v240
	v_mul_f32_e32 v66, v66, v240
	v_mul_f32_e32 v67, v67, v240
	v_mul_f32_e32 v68, v68, v241
	v_mul_f32_e32 v69, v69, v241
	v_mul_f32_e32 v70, v70, v241
	v_mul_f32_e32 v71, v71, v241
	v_mul_f32_e32 v72, v72, v242
	v_mul_f32_e32 v73, v73, v242
	v_mul_f32_e32 v74, v74, v242
	v_mul_f32_e32 v75, v75, v242
	v_mul_f32_e32 v76, v76, v243
	v_mul_f32_e32 v77, v77, v243
	v_mul_f32_e32 v78, v78, v243
	v_mul_f32_e32 v79, v79, v243
	v_cndmask_b32_e64 v67, v67, 0, s[18:19]
	v_cndmask_b32_e64 v71, v71, 0, s[18:19]
	v_cndmask_b32_e64 v75, v75, 0, s[18:19]
	v_cndmask_b32_e64 v79, v79, 0, s[18:19]
	v_cvt_pk_bf16_f32 v8, v64, v68
	v_cvt_pk_bf16_f32 v9, v72, v76
	v_cvt_pk_bf16_f32 v10, v65, v69
	v_cvt_pk_bf16_f32 v11, v73, v77
	v_cvt_pk_bf16_f32 v12, v66, v70
	v_cvt_pk_bf16_f32 v13, v74, v78
	v_cvt_pk_bf16_f32 v14, v67, v71
	v_cvt_pk_bf16_f32 v15, v75, v79
	s_lshl_b32 s16, s8, 7
	s_add_u32 s16, s16, 0x2d00000
	s_add_u32 s12, s4, s16
	s_addc_u32 s13, s5, 0
	global_store_dwordx2 v251, v[8:9], s[12:13]
	global_store_dwordx2 v251, v[10:11], s[12:13] offset:128
	global_store_dwordx2 v251, v[12:13], s[12:13] offset:256
	global_store_dwordx2 v251, v[14:15], s[12:13] offset:384
	s_branch .LBB0_784
